# MLA attention QK: K-fragment LDS reads issued ahead into spare quads (removes exposed LDS latency between MFMAs)
# baseline (speedup 1.0000x reference)
; #define LAS __attribute__((address_space(3)))
; template <int TYPE, int ND0, int KSTR> __device__ __forceinline__ void tile(LAS unsigned char* lds, int buf, int t, int w_lo, int w_hi, int n, int qrel, int lane, int r32, int hi,
;         const bf16x8 (&qr)[ND0], float& m_run, float& l_run, f32x16& o0, f32x16& o1, f32x16& negm) {
;     const LAS unsigned char* kb = lds + KOFF + buf * KBUF + r32 * KSTR + hi * 16;
;     bf16x8 ka[ND0], kc[ND0];
; #pragma unroll
;     for (int d0 = 0; d0 < ND0; ++d0) { ka[d0] = *(const LAS bf16x8*)(kb + d0 * 32); kc[d0] = *(const LAS bf16x8*)(kb + 32 * KSTR + d0 * 32); }
;     const LAS unsigned char* vb = lds + VOFF + buf * VBUF + (4 * hi + ((lane & 15) >> 2)) * VSTR + (16 * ((lane >> 4) & 1) + 4 * (lane & 3)) * 2;
;     s16x4 vf[4][4];
; #pragma unroll
;     for (int ks = 0; ks < 4; ++ks) { vf[ks][0] = vtr(vb + (16 * ks) * VSTR); vf[ks][1] = vtr(vb + (16 * ks + 8) * VSTR); vf[ks][2] = vtr(vb + (16 * ks) * VSTR + 64); vf[ks][3] = vtr(vb + (16 * ks + 8) * VSTR + 64); }
;     f32x4 kbv[8];
;     if (TYPE == 0) { const LAS f32x4* kbi = (const LAS f32x4*)(lds + KBOFF + buf * 256);
; #pragma unroll
;         for (int g = 0; g < 4; ++g) { kbv[g] = kbi[2 * g + hi]; kbv[4 + g] = kbi[8 + 2 * g + hi]; } }
;     asm volatile("" ::: "memory");
;     const int rel = n - t;
;     f32x16 cin = negm;
;     if (TYPE == 2 && rel >= 5) { const float c = ((const LAS float*)(lds + RELOFF))[512];
; #pragma unroll
;         for (int r = 0; r < 16; ++r) cin[r] += c; }
;     f32x16 p0 = cin, p1 = cin;
; #pragma unroll
;     for (int d0 = 0; d0 < ND0; ++d0) {
;         p0 = __builtin_amdgcn_mfma_f32_32x32x16_bf16(ka[d0], qr[d0], p0, 0, 0, 0);
;         p1 = __builtin_amdgcn_mfma_f32_32x32x16_bf16(kc[d0], qr[d0], p1, 0, 0, 0);
;     }
;     if (TYPE == 0) {
; #pragma unroll
;         for (int g = 0; g < 4; ++g)
; #pragma unroll
;             for (int j = 0; j < 4; ++j) { p0[4 * g + j] += kbv[g][j]; p1[4 * g + j] += kbv[4 + g][j]; }
;         if (t == w_hi) {
; #pragma unroll
;             for (int r = 0; r < 16; ++r) { const int kr_ = crow(r, hi); if (kr_ > qrel) p0[r] = -1e30f; if (kr_ + 32 > qrel) p1[r] = -1e30f; }
;         }
;     }
;     if (TYPE == 2 && rel < 5) {
;         const LAS float* rb = (const LAS float*)(lds + RELOFF) + (qrel + 64 * rel + 256 - 4 * hi - 59);
; #pragma unroll
.LBB0_704:
	s_sub_i32 s44, s4, 64
	s_lshl_b64 s[6:7], s[44:45], 10
	s_waitcnt vmcnt(3)
	v_lshl_add_u64 v[2:3], v[174:175], 0, s[6:7]
	v_lshl_add_u64 v[4:5], v[176:177], 0, s[6:7]
	s_lshl_b64 s[6:7], s[44:45], 6
	global_load_dwordx4 v[6:9], v[2:3], off
	global_load_dwordx4 v[10:13], v[4:5], off
	v_lshl_add_u64 v[2:3], v[180:181], 0, s[6:7]
	global_load_dwordx4 v[2:5], v[2:3], off
	s_cmp_gt_i32 s3, s9
	s_cbranch_scc1 .LBB0_710
	v_add_u32_e32 v0, v227, v170
	ds_read_b128 v[80:83], v0
	s_waitcnt vmcnt(6)
	ds_read_b128 v[108:111], v0 offset:32
	ds_read_b128 v[112:115], v0 offset:6656
	ds_read_b128 v[116:119], v0 offset:6688
	ds_read_b128 v[212:215], v0 offset:64
	ds_read_b128 v[232:235], v0 offset:96
	ds_read_b128 v[240:243], v0 offset:6720
	ds_read_b128 v[244:247], v0 offset:6752
	s_cmp_lg_u32 s3, 0
	s_waitcnt lgkmcnt(7)
	v_mfma_f32_32x32x16_bf16 v[64:79], v[80:83], v[140:143], v[48:63]
	s_waitcnt lgkmcnt(5)
	v_mfma_f32_32x32x16_bf16 v[80:95], v[112:115], v[140:143], v[48:63]
	ds_read_b128 v[112:115], v0 offset:160
	v_mfma_f32_32x32x16_bf16 v[64:79], v[108:111], v[136:139], v[64:79]
	ds_read_b128 v[108:111], v0 offset:6784
	s_waitcnt lgkmcnt(6)
	v_mfma_f32_32x32x16_bf16 v[80:95], v[116:119], v[136:139], v[80:95]
	ds_read_b128 v[116:119], v0 offset:128
	ds_read_b128 v[182:185], v0 offset:6816
	s_waitcnt lgkmcnt(7)
	v_mfma_f32_32x32x16_bf16 v[64:79], v[212:215], v[132:135], v[64:79]
	s_waitcnt lgkmcnt(5)
	v_mfma_f32_32x32x16_bf16 v[80:95], v[240:243], v[132:135], v[80:95]
	s_waitcnt vmcnt(5)
	v_mfma_f32_32x32x16_bf16 v[64:79], v[232:235], v[128:131], v[64:79]
	s_waitcnt lgkmcnt(4)
	v_mfma_f32_32x32x16_bf16 v[80:95], v[244:247], v[128:131], v[80:95]
	s_waitcnt vmcnt(4) lgkmcnt(1)
	v_mfma_f32_32x32x16_bf16 v[64:79], v[116:119], v[124:127], v[64:79]
	v_add_u32_e32 v0, v228, v229
	ds_read_b64_tr_b16 v[160:161], v0 offset:26624
	ds_read_b64_tr_b16 v[162:163], v0 offset:28160
	ds_read_b64_tr_b16 v[158:159], v0 offset:28224
	ds_read_b64_tr_b16 v[156:157], v0 offset:26688
	ds_read_b64_tr_b16 v[152:153], v0 offset:29696
	ds_read_b64_tr_b16 v[154:155], v0 offset:31232
	ds_read_b64_tr_b16 v[150:151], v0 offset:31296
	ds_read_b64_tr_b16 v[148:149], v0 offset:29760
	s_waitcnt lgkmcnt(9)
	v_mfma_f32_32x32x16_bf16 v[80:95], v[108:111], v[124:127], v[80:95]
	s_waitcnt vmcnt(3)
	v_mfma_f32_32x32x16_bf16 v[64:79], v[112:115], v[120:123], v[64:79]
	ds_read_b64_tr_b16 v[116:117], v0 offset:32768
	ds_read_b64_tr_b16 v[118:119], v0 offset:34304
	ds_read_b64_tr_b16 v[146:147], v0 offset:34368
	ds_read_b64_tr_b16 v[144:145], v0 offset:32832
	ds_read_b64_tr_b16 v[112:113], v0 offset:35840
	ds_read_b64_tr_b16 v[114:115], v0 offset:37376
	ds_read_b64_tr_b16 v[110:111], v0 offset:37440
	ds_read_b64_tr_b16 v[108:109], v0 offset:35904
	s_waitcnt lgkmcnt(14)
	v_mfma_f32_32x32x16_bf16 v[80:95], v[182:185], v[120:123], v[80:95]
	s_cbranch_scc1 .LBB0_707
	s_nop 10
	v_max_f32_e32 v0, v81, v81
	v_max_f32_e32 v14, v65, v65
	v_max_f32_e32 v0, v14, v0
	v_max_f32_e32 v14, v82, v82
	v_max_f32_e32 v15, v66, v66
	v_max_f32_e32 v14, v15, v14
	v_max_f32_e32 v15, v83, v83
	v_max_f32_e32 v48, v67, v67
	v_max3_f32 v0, v64, v80, v0
	v_max_f32_e32 v15, v48, v15
	v_max3_f32 v0, v0, v14, v15
	v_max_f32_e32 v14, v84, v84
	v_max_f32_e32 v15, v68, v68
	v_max_f32_e32 v14, v15, v14
	v_max_f32_e32 v15, v85, v85
	v_max_f32_e32 v48, v69, v69
	v_max_f32_e32 v15, v48, v15
	v_max3_f32 v0, v0, v14, v15
	v_max_f32_e32 v14, v86, v86
	v_max_f32_e32 v15, v70, v70
	v_max_f32_e32 v14, v15, v14
	v_max_f32_e32 v15, v87, v87
	v_max_f32_e32 v48, v71, v71
	v_max_f32_e32 v15, v48, v15
	v_max3_f32 v0, v0, v14, v15
	v_max_f32_e32 v14, v88, v88
	v_max_f32_e32 v15, v72, v72
	v_max_f32_e32 v14, v15, v14
	v_max_f32_e32 v15, v89, v89
	v_max_f32_e32 v48, v73, v73
	v_max_f32_e32 v15, v48, v15
	v_max3_f32 v0, v0, v14, v15
	v_max_f32_e32 v14, v90, v90
	v_max_f32_e32 v15, v74, v74
	v_max_f32_e32 v14, v15, v14
	v_max_f32_e32 v15, v91, v91
	v_max_f32_e32 v48, v75, v75
	v_max_f32_e32 v15, v48, v15
	v_max3_f32 v0, v0, v14, v15
	v_max_f32_e32 v14, v92, v92
	v_max_f32_e32 v15, v76, v76
	v_max_f32_e32 v14, v15, v14
	v_max_f32_e32 v15, v93, v93
	v_max_f32_e32 v48, v77, v77
	v_max_f32_e32 v15, v48, v15
	v_max3_f32 v0, v0, v14, v15
	v_max_f32_e32 v14, v94, v94
	v_max_f32_e32 v15, v78, v78
	v_max_f32_e32 v14, v15, v14
	v_max_f32_e32 v15, v95, v95
	v_max_f32_e32 v48, v79, v79
	v_max_f32_e32 v15, v48, v15
	v_max3_f32 v0, v0, v14, v15
	v_mov_b32_e32 v14, v0
	s_nop 1
	v_permlane32_swap_b32_e32 v0, v14
	v_max_f32_e32 v14, v14, v14
	v_max_f32_e32 v0, v0, v0
	v_max_f32_e32 v171, v0, v14
	v_xor_b32_e32 v48, 0x80000000, v171
	v_sub_f32_e32 v79, v79, v171
	v_sub_f32_e32 v78, v78, v171
	v_sub_f32_e32 v77, v77, v171
	v_sub_f32_e32 v76, v76, v171
	v_sub_f32_e32 v75, v75, v171
	v_sub_f32_e32 v74, v74, v171
	v_sub_f32_e32 v73, v73, v171
	v_sub_f32_e32 v72, v72, v171
	v_sub_f32_e32 v71, v71, v171
	v_sub_f32_e32 v70, v70, v171
	v_sub_f32_e32 v69, v69, v171
	v_sub_f32_e32 v68, v68, v171
	v_sub_f32_e32 v67, v67, v171
	v_sub_f32_e32 v66, v66, v171
	v_sub_f32_e32 v65, v65, v171
	v_sub_f32_e32 v64, v64, v171
	v_sub_f32_e32 v95, v95, v171
	v_sub_f32_e32 v94, v94, v171
	v_sub_f32_e32 v93, v93, v171
	v_sub_f32_e32 v92, v92, v171
	v_sub_f32_e32 v91, v91, v171
	v_sub_f32_e32 v90, v90, v171
	v_sub_f32_e32 v89, v89, v171
	v_sub_f32_e32 v88, v88, v171
	v_sub_f32_e32 v87, v87, v171
	v_sub_f32_e32 v86, v86, v171
	v_sub_f32_e32 v85, v85, v171
	v_sub_f32_e32 v84, v84, v171
	v_sub_f32_e32 v83, v83, v171
	v_sub_f32_e32 v82, v82, v171
	v_sub_f32_e32 v81, v81, v171
	v_sub_f32_e32 v80, v80, v171
	v_mov_b32_e32 v49, v48
	v_mov_b32_e32 v50, v48
	v_mov_b32_e32 v51, v48
	v_mov_b32_e32 v52, v48
	v_mov_b32_e32 v53, v48
	v_mov_b32_e32 v54, v48
	v_mov_b32_e32 v55, v48
	v_mov_b32_e32 v56, v48
	v_mov_b32_e32 v57, v48
	v_mov_b32_e32 v58, v48
	v_mov_b32_e32 v59, v48
	v_mov_b32_e32 v60, v48
	v_mov_b32_e32 v61, v48
	v_mov_b32_e32 v62, v48
	v_mov_b32_e32 v63, v48

; #define LAS __attribute__((address_space(3)))
; __device__ __forceinline__ s16x4 vtr(const LAS unsigned char* p) { return __builtin_bit_cast(s16x4, __builtin_amdgcn_ds_read_tr16_b64_v4i16((LAS v4i16_t*)p)); }
; template <int TYPE, int ND0, int KSTR> __device__ __forceinline__ void tile(LAS unsigned char* lds, int buf, int t, int w_lo, int w_hi, int n, int qrel, int lane, int r32, int hi,
;         const bf16x8 (&qr)[ND0], float& m_run, float& l_run, f32x16& o0, f32x16& o1, f32x16& negm) {
;     const LAS unsigned char* kb = lds + KOFF + buf * KBUF + r32 * KSTR + hi * 16;
;     bf16x8 ka[ND0], kc[ND0];
; #pragma unroll
;     for (int d0 = 0; d0 < ND0; ++d0) { ka[d0] = *(const LAS bf16x8*)(kb + d0 * 32); kc[d0] = *(const LAS bf16x8*)(kb + 32 * KSTR + d0 * 32); }
;     const LAS unsigned char* vb = lds + VOFF + buf * VBUF + (4 * hi + ((lane & 15) >> 2)) * VSTR + (16 * ((lane >> 4) & 1) + 4 * (lane & 3)) * 2;
;     s16x4 vf[4][4];
; #pragma unroll
;     for (int ks = 0; ks < 4; ++ks) { vf[ks][0] = vtr(vb + (16 * ks) * VSTR); vf[ks][1] = vtr(vb + (16 * ks + 8) * VSTR); vf[ks][2] = vtr(vb + (16 * ks) * VSTR + 64); vf[ks][3] = vtr(vb + (16 * ks + 8) * VSTR + 64); }
;     f32x4 kbv[8];
;     if (TYPE == 0) { const LAS f32x4* kbi = (const LAS f32x4*)(lds + KBOFF + buf * 256);
; #pragma unroll
;         for (int g = 0; g < 4; ++g) { kbv[g] = kbi[2 * g + hi]; kbv[4 + g] = kbi[8 + 2 * g + hi]; } }
;     asm volatile("" ::: "memory");
;     const int rel = n - t;
;     f32x16 cin = negm;
;     if (TYPE == 2 && rel >= 5) { const float c = ((const LAS float*)(lds + RELOFF))[512];
; #pragma unroll
;         for (int r = 0; r < 16; ++r) cin[r] += c; }
;     f32x16 p0 = cin, p1 = cin;
; #pragma unroll
;     for (int d0 = 0; d0 < ND0; ++d0) {
;         p0 = __builtin_amdgcn_mfma_f32_32x32x16_bf16(ka[d0], qr[d0], p0, 0, 0, 0);
;         p1 = __builtin_amdgcn_mfma_f32_32x32x16_bf16(kc[d0], qr[d0], p1, 0, 0, 0);
;     }
;     ...
;     float ls = 0.f;
; #pragma unroll
;     for (int r = 0; r < 16; ++r) { p0[r] = __builtin_amdgcn_exp2f(p0[r]); p1[r] = __builtin_amdgcn_exp2f(p1[r]); ls += p0[r] + p1[r]; }
;     const float lrow = hsum(ls);
;     if (__builtin_amdgcn_ballot_w64(lrow > 1099511627776.0f) != 0ull) {
.LBB0_712:
	s_or_b64 exec, exec, s[6:7]
	s_mov_b32 s5, s45
	s_lshl_b64 s[6:7], s[4:5], 10
	v_lshl_add_u64 v[14:15], v[174:175], 0, s[6:7]
	v_lshl_add_u64 v[64:65], v[176:177], 0, s[6:7]
	s_lshl_b64 s[6:7], s[4:5], 6
	s_waitcnt lgkmcnt(0)
	s_barrier
	global_load_dwordx4 v[96:99], v[14:15], off
	global_load_dwordx4 v[104:107], v[64:65], off
	v_lshl_add_u64 v[14:15], v[180:181], 0, s[6:7]
	global_load_dwordx4 v[100:103], v[14:15], off
	s_cmp_ge_i32 s3, s9
	s_cbranch_scc1 .LBB0_716
	v_add_u32_e32 v0, v227, v170
	ds_read_b128 v[80:83], v0 offset:13312
	ds_read_b128 v[108:111], v0 offset:13344
	ds_read_b128 v[112:115], v0 offset:19968
	ds_read_b128 v[116:119], v0 offset:20000
	ds_read_b128 v[212:215], v0 offset:13376
	ds_read_b128 v[232:235], v0 offset:13408
	ds_read_b128 v[240:243], v0 offset:20032
	ds_read_b128 v[244:247], v0 offset:20064
	v_add_u32_e32 v15, v228, v229
	s_mov_b32 s5, 0x53800000
	s_waitcnt lgkmcnt(7)
	v_mfma_f32_32x32x16_bf16 v[64:79], v[80:83], v[140:143], v[48:63]
	s_waitcnt lgkmcnt(5)
	v_mfma_f32_32x32x16_bf16 v[80:95], v[112:115], v[140:143], v[48:63]
	ds_read_b128 v[112:115], v0 offset:13472
	v_mfma_f32_32x32x16_bf16 v[64:79], v[108:111], v[136:139], v[64:79]
	ds_read_b128 v[108:111], v0 offset:20096
	s_waitcnt lgkmcnt(6)
	v_mfma_f32_32x32x16_bf16 v[80:95], v[116:119], v[136:139], v[80:95]
	ds_read_b128 v[116:119], v0 offset:13440
	s_waitcnt lgkmcnt(6)
	v_mfma_f32_32x32x16_bf16 v[64:79], v[212:215], v[132:135], v[64:79]
	ds_read_b128 v[212:215], v0 offset:20128
	s_waitcnt lgkmcnt(5)
	v_mfma_f32_32x32x16_bf16 v[80:95], v[240:243], v[132:135], v[80:95]
	v_mfma_f32_32x32x16_bf16 v[64:79], v[232:235], v[128:131], v[64:79]
	s_waitcnt lgkmcnt(4)
	v_mfma_f32_32x32x16_bf16 v[80:95], v[244:247], v[128:131], v[80:95]
	s_waitcnt lgkmcnt(1)
	v_mfma_f32_32x32x16_bf16 v[64:79], v[116:119], v[124:127], v[64:79]
	v_mfma_f32_32x32x16_bf16 v[80:95], v[108:111], v[124:127], v[80:95]
	s_waitcnt vmcnt(6)
	v_mfma_f32_32x32x16_bf16 v[64:79], v[112:115], v[120:123], v[64:79]
	ds_read_b64_tr_b16 v[112:113], v15 offset:38912
	ds_read_b64_tr_b16 v[114:115], v15 offset:40448
	ds_read_b64_tr_b16 v[110:111], v15 offset:40512
	ds_read_b64_tr_b16 v[108:109], v15 offset:38976
	s_waitcnt lgkmcnt(4)
	v_mfma_f32_32x32x16_bf16 v[80:95], v[212:215], v[120:123], v[80:95]
	s_nop 5
	v_exp_f32_e32 v146, v64
	v_exp_f32_e32 v190, v65
	v_exp_f32_e32 v148, v66
	v_exp_f32_e32 v194, v67
	v_exp_f32_e32 v150, v68
	v_exp_f32_e32 v198, v69
	v_exp_f32_e32 v154, v70
	v_exp_f32_e32 v14, v80
	v_exp_f32_e32 v0, v81
	v_exp_f32_e32 v116, v82
	v_exp_f32_e32 v118, v84
	v_add_f32_e32 v191, v146, v14
	v_pk_add_f32 v[64:65], v[190:191], v[0:1]
	v_add_f32_e32 v195, v148, v116
	v_pk_add_f32 v[162:163], v[64:65], v[64:65] op_sel_hi:[0,1]
	v_exp_f32_e32 v162, v83
	v_add_f32_e32 v199, v150, v118
	v_exp_f32_e32 v144, v86
	v_exp_f32_e32 v200, v71
	v_pk_add_f32 v[64:65], v[194:195], v[162:163]
	v_exp_f32_e32 v152, v72
	v_pk_add_f32 v[182:183], v[64:65], v[64:65] op_sel_hi:[0,1]
	v_exp_f32_e32 v182, v85
	v_add_f32_e32 v201, v154, v144
	v_exp_f32_e32 v88, v88
	v_exp_f32_e32 v202, v73
	v_pk_add_f32 v[64:65], v[198:199], v[182:183]
	v_exp_f32_e32 v156, v74
	v_pk_add_f32 v[184:185], v[64:65], v[64:65] op_sel_hi:[0,1]
	v_exp_f32_e32 v184, v87
	v_add_f32_e32 v203, v152, v88
	v_exp_f32_e32 v90, v90
	v_exp_f32_e32 v204, v75
	v_pk_add_f32 v[64:65], v[200:201], v[184:185]
	v_exp_f32_e32 v158, v76
	v_pk_add_f32 v[186:187], v[64:65], v[64:65] op_sel_hi:[0,1]
	v_exp_f32_e32 v186, v89
	v_add_f32_e32 v205, v156, v90
	v_exp_f32_e32 v92, v92
	v_exp_f32_e32 v206, v77
	v_pk_add_f32 v[64:65], v[202:203], v[186:187]
	v_exp_f32_e32 v160, v78
	v_pk_add_f32 v[188:189], v[64:65], v[64:65] op_sel_hi:[0,1]
	v_exp_f32_e32 v188, v91
	v_add_f32_e32 v207, v158, v92
	v_exp_f32_e32 v94, v94
	v_exp_f32_e32 v220, v79
	v_pk_add_f32 v[72:73], v[204:205], v[188:189]
	ds_read_b64_tr_b16 v[84:85], v15 offset:41984
	ds_read_b64_tr_b16 v[86:87], v15 offset:43520
	ds_read_b64_tr_b16 v[82:83], v15 offset:43584
	ds_read_b64_tr_b16 v[80:81], v15 offset:42048
	v_pk_add_f32 v[192:193], v[72:73], v[72:73] op_sel_hi:[0,1]
	v_exp_f32_e32 v192, v93
	ds_read_b64_tr_b16 v[68:69], v15 offset:45056
	ds_read_b64_tr_b16 v[70:71], v15 offset:46592
	ds_read_b64_tr_b16 v[66:67], v15 offset:46656
	ds_read_b64_tr_b16 v[64:65], v15 offset:45120
	v_add_f32_e32 v221, v160, v94
	v_pk_add_f32 v[72:73], v[206:207], v[192:193]
	s_nop 0
	v_pk_add_f32 v[196:197], v[72:73], v[72:73] op_sel_hi:[0,1]
	v_exp_f32_e32 v196, v95
	ds_read_b64_tr_b16 v[76:77], v15 offset:48128
	ds_read_b64_tr_b16 v[78:79], v15 offset:49664
	ds_read_b64_tr_b16 v[74:75], v15 offset:49728
	ds_read_b64_tr_b16 v[72:73], v15 offset:48192
	v_pk_add_f32 v[208:209], v[220:221], v[196:197]
	s_nop 0
	v_pk_add_f32 v[222:223], v[208:209], v[208:209] op_sel:[0,1] op_sel_hi:[1,0]
	s_nop 0
	v_mov_b32_e32 v15, v222
	v_mov_b32_e32 v89, v222
	s_nop 1
	v_permlane32_swap_b32_e32 v15, v89
	v_add_f32_e32 v15, v15, v89
	v_cmp_lt_f32_e32 vcc, s5, v15
	s_cbranch_vccz .LBB0_715
; __device__ __forceinline__ float hmax(float m) { auto rr = __builtin_amdgcn_permlane32_swap(__float_as_uint(m), __float_as_uint(m), false, false); return fmaxf(__uint_as_float(rr[0]), __uint_as_float(rr[1])); }
; template <int TYPE, int ND0, int KSTR> __device__ __forceinline__ void tile(LAS unsigned char* lds, int buf, int t, int w_lo, int w_hi, int n, int qrel, int lane, int r32, int hi,
;         const bf16x8 (&qr)[ND0], float& m_run, float& l_run, f32x16& o0, f32x16& o1, f32x16& negm) {
;     ...
;         float pm = fmaxf(p0[0], p1[0]);
; #pragma unroll
;         for (int r = 1; r < 16; ++r) pm = fmaxf(pm, fmaxf(p0[r], p1[r]));
;         pm = hmax(pm);
;         const float dl = (lrow > 1099511627776.0f) ? __builtin_amdgcn_logf(pm) : 0.f;
;         const float sc = __builtin_amdgcn_exp2f(-dl);
;         m_run += dl; l_run *= sc; ls *= sc;
; #pragma unroll
;         for (int r = 0; r < 16; ++r) { p0[r] *= sc; p1[r] *= sc; o0[r] *= sc; o1[r] *= sc; negm[r] = -m_run; }
;     }
	v_max_f32_e32 v15, v0, v0
	v_max_f32_e32 v48, v190, v190
	v_max_f32_e32 v15, v48, v15
	v_max_f32_e32 v48, v116, v116
	v_max_f32_e32 v49, v148, v148
	v_max_f32_e32 v48, v49, v48
	v_max_f32_e32 v49, v162, v162
	v_max_f32_e32 v50, v194, v194
	v_max3_f32 v15, v146, v14, v15
	v_max_f32_e32 v49, v50, v49
	v_max3_f32 v15, v15, v48, v49
	v_max_f32_e32 v48, v118, v118
	v_max_f32_e32 v49, v150, v150
	v_max_f32_e32 v48, v49, v48
	v_max_f32_e32 v49, v182, v182
	v_max_f32_e32 v50, v198, v198
	v_max_f32_e32 v49, v50, v49
	v_max3_f32 v15, v15, v48, v49
	v_max_f32_e32 v48, v144, v144
	v_max_f32_e32 v49, v154, v154
	v_max_f32_e32 v48, v49, v48
	v_max_f32_e32 v49, v184, v184
	v_max_f32_e32 v50, v200, v200
	v_max_f32_e32 v49, v50, v49
	v_max3_f32 v15, v15, v48, v49
	v_max_f32_e32 v48, v88, v88
	v_max_f32_e32 v49, v152, v152
	v_max_f32_e32 v48, v49, v48
	v_max_f32_e32 v49, v186, v186
	v_max_f32_e32 v50, v202, v202
	v_max_f32_e32 v49, v50, v49
	v_max3_f32 v15, v15, v48, v49
	v_max_f32_e32 v48, v90, v90
	v_max_f32_e32 v49, v156, v156
	v_max_f32_e32 v48, v49, v48
	v_max_f32_e32 v49, v188, v188
	v_max_f32_e32 v50, v204, v204
	v_max_f32_e32 v49, v50, v49
	v_max3_f32 v15, v15, v48, v49
	v_max_f32_e32 v48, v92, v92
	v_max_f32_e32 v49, v158, v158
	v_max_f32_e32 v48, v49, v48
	v_max_f32_e32 v49, v192, v192
	v_max_f32_e32 v50, v206, v206
	v_max_f32_e32 v49, v50, v49
	v_max3_f32 v15, v15, v48, v49
	v_max_f32_e32 v48, v94, v94
	v_max_f32_e32 v49, v160, v160
	v_max_f32_e32 v48, v49, v48
	v_max_f32_e32 v49, v196, v196
	v_max_f32_e32 v50, v220, v220
	v_max_f32_e32 v49, v50, v49
	v_max3_f32 v15, v15, v48, v49
	v_mov_b32_e32 v48, v15
	s_nop 1
	v_permlane32_swap_b32_e32 v15, v48
	v_max_f32_e32 v48, v48, v48
	v_max_f32_e32 v15, v15, v15
	v_max_f32_e32 v15, v15, v48
	v_log_f32_e32 v15, v15
	v_mov_b32_e32 v167, v222
	v_mov_b32_e32 v161, v220
	v_mov_b32_e32 v159, v206
	v_cndmask_b32_e32 v15, 0, v15, vcc
	v_exp_f32_e64 v208, -v15
	v_add_f32_e32 v171, v171, v15
	v_mov_b32_e32 v157, v204
	v_mov_b32_e32 v153, v202
	v_mov_b32_e32 v155, v200
	v_mov_b32_e32 v151, v198
	v_mov_b32_e32 v149, v194
	v_mov_b32_e32 v147, v190
	v_mov_b32_e32 v95, v196
	v_mov_b32_e32 v93, v192
	v_mov_b32_e32 v91, v188
	v_mov_b32_e32 v89, v186
	v_mov_b32_e32 v145, v184
	v_mov_b32_e32 v119, v182
	v_mov_b32_e32 v117, v162
	v_mov_b32_e32 v15, v0
	v_xor_b32_e32 v48, 0x80000000, v171
	v_pk_mul_f32 v[160:161], v[160:161], v[208:209] op_sel_hi:[1,0]
	v_pk_mul_f32 v[158:159], v[158:159], v[208:209] op_sel_hi:[1,0]
	v_pk_mul_f32 v[156:157], v[156:157], v[208:209] op_sel_hi:[1,0]
	v_pk_mul_f32 v[152:153], v[152:153], v[208:209] op_sel_hi:[1,0]
	v_pk_mul_f32 v[154:155], v[154:155], v[208:209] op_sel_hi:[1,0]
	v_pk_mul_f32 v[150:151], v[150:151], v[208:209] op_sel_hi:[1,0]
	v_pk_mul_f32 v[148:149], v[148:149], v[208:209] op_sel_hi:[1,0]
	v_pk_mul_f32 v[146:147], v[146:147], v[208:209] op_sel_hi:[1,0]
	v_pk_mul_f32 v[94:95], v[94:95], v[208:209] op_sel_hi:[1,0]
	v_pk_mul_f32 v[92:93], v[92:93], v[208:209] op_sel_hi:[1,0]
	v_pk_mul_f32 v[90:91], v[90:91], v[208:209] op_sel_hi:[1,0]
	v_pk_mul_f32 v[88:89], v[88:89], v[208:209] op_sel_hi:[1,0]
	v_pk_mul_f32 v[144:145], v[144:145], v[208:209] op_sel_hi:[1,0]
	v_pk_mul_f32 v[118:119], v[118:119], v[208:209] op_sel_hi:[1,0]
	v_pk_mul_f32 v[116:117], v[116:117], v[208:209] op_sel_hi:[1,0]
	v_pk_mul_f32 v[14:15], v[14:15], v[208:209] op_sel_hi:[1,0]
	v_pk_mul_f32 v[166:167], v[166:167], v[208:209] op_sel_hi:[1,0]
	v_pk_mul_f32 v[46:47], v[46:47], v[208:209] op_sel_hi:[1,0]
	v_pk_mul_f32 v[44:45], v[44:45], v[208:209] op_sel_hi:[1,0]
	v_pk_mul_f32 v[42:43], v[42:43], v[208:209] op_sel_hi:[1,0]
	v_pk_mul_f32 v[40:41], v[40:41], v[208:209] op_sel_hi:[1,0]
	v_pk_mul_f32 v[38:39], v[38:39], v[208:209] op_sel_hi:[1,0]
	v_pk_mul_f32 v[36:37], v[36:37], v[208:209] op_sel_hi:[1,0]
	v_pk_mul_f32 v[34:35], v[34:35], v[208:209] op_sel_hi:[1,0]
	v_pk_mul_f32 v[32:33], v[32:33], v[208:209] op_sel_hi:[1,0]
	v_pk_mul_f32 v[30:31], v[30:31], v[208:209] op_sel_hi:[1,0]
	v_pk_mul_f32 v[28:29], v[28:29], v[208:209] op_sel_hi:[1,0]
	v_pk_mul_f32 v[26:27], v[26:27], v[208:209] op_sel_hi:[1,0]
	v_pk_mul_f32 v[24:25], v[24:25], v[208:209] op_sel_hi:[1,0]
	v_pk_mul_f32 v[22:23], v[22:23], v[208:209] op_sel_hi:[1,0]
	v_pk_mul_f32 v[20:21], v[20:21], v[208:209] op_sel_hi:[1,0]
	v_pk_mul_f32 v[18:19], v[18:19], v[208:209] op_sel_hi:[1,0]
	v_pk_mul_f32 v[16:17], v[16:17], v[208:209] op_sel_hi:[1,0]
	v_mov_b32_e32 v49, v48
	v_mov_b32_e32 v50, v48
	v_mov_b32_e32 v51, v48
	v_mov_b32_e32 v52, v48
	v_mov_b32_e32 v53, v48
	v_mov_b32_e32 v54, v48
	v_mov_b32_e32 v55, v48
	v_mov_b32_e32 v56, v48
	v_mov_b32_e32 v57, v48
	v_mov_b32_e32 v58, v48
	v_mov_b32_e32 v59, v48
	v_mov_b32_e32 v60, v48
	v_mov_b32_e32 v61, v48
	v_mov_b32_e32 v62, v48
	v_mov_b32_e32 v63, v48
	v_mov_b32_e32 v0, v15
	v_mov_b32_e32 v162, v117
	v_mov_b32_e32 v182, v119
	v_mov_b32_e32 v184, v145
	v_mov_b32_e32 v186, v89
	v_mov_b32_e32 v188, v91
	v_mov_b32_e32 v192, v93
	v_mov_b32_e32 v196, v95
	v_mov_b32_e32 v190, v147
	v_mov_b32_e32 v194, v149
	v_mov_b32_e32 v198, v151
	v_mov_b32_e32 v200, v155
	v_mov_b32_e32 v202, v153
	v_mov_b32_e32 v204, v157
	v_mov_b32_e32 v206, v159
	v_mov_b32_e32 v220, v161
	v_mov_b32_e32 v222, v167
